# baseline (speedup 1.0000x reference)
; __device__ __forceinline__ void finishSM(f32x16& p0, f32x16& p1, float alpha, float& l_reg, bf16x8& pa0, bf16x8& pa1, bf16x8& pa2, bf16x8& pa3) {
; #pragma unroll
;   for (int r = 0; r < 16; ++r) p1[r] = __builtin_amdgcn_exp2f(p1[r]);
;   float ps = 0;
; #pragma unroll
;   for (int r = 0; r < 16; ++r) ps += p0[r];
; #pragma unroll
;   for (int r = 0; r < 16; ++r) ps += p1[r];
;   { auto rr = __builtin_amdgcn_permlane32_swap(__float_as_uint(ps), __float_as_uint(ps), false, false);
;     ps = __uint_as_float(rr[0]) + __uint_as_float(rr[1]); }
;   l_reg = l_reg * alpha + ps;
;     ...
;   PK4(p0, 0, pa0); PK4(p0, 8, pa1); PK4(p1, 0, pa2); PK4(p1, 8, pa3);
;     ...
; }
; template <int BUFOFF>
; __device__ __forceinline__ void qkt_mla(f32x16& p0, f32x16& p1, const int* ka, const bf16x8* qr, const char* qlds) {
;   typedef __attribute__((address_space(3))) const bf16x8* lp;
;   p0 = f32x16{}; p1 = f32x16{};
; #pragma unroll
;   for (int d0 = 0; d0 < 12; ++d0) {
;     const int a = ka[d0 & 3] + (d0 >> 2) * 128 + BUFOFF;
;     const bf16x8 b0 = *(lp)(a), b1 = *(lp)(a + 12288);
;     bf16x8 qf;
;     qf = qr[d0];
;     p0 = __builtin_amdgcn_mfma_f32_32x32x16_bf16(b0, qf, p0, 0, 0, 0);
;     p1 = __builtin_amdgcn_mfma_f32_32x32x16_bf16(b1, qf, p1, 0, 0, 0);
;   }
; }
.LBB0_115:
	s_mov_b32 s55, s43
	s_mov_b32 s43, s52
	ds_read_b128 v[64:67], v169 offset:24576
	ds_read_b128 v[68:71], v169 offset:36864
	ds_read_b128 v[214:217], v190 offset:24576
	ds_read_b128 v[218:221], v190 offset:36864
	v_mov_b32_e32 v196, v158
	v_mov_b32_e32 v222, v147
	v_mov_b32_e32 v223, v154
	v_mov_b32_e32 v224, v155
	v_add_f32_e32 v253, v199, v200
	v_add_f32_e32 v243, v211, v145
	v_add_f32_e32 v244, v201, v203
	v_add_f32_e32 v245, v213, v210
	s_waitcnt lgkmcnt(0)
	v_mfma_f32_32x32x16_bf16 v[80:95], v[64:67], v[140:143], v[226:241]
	v_add_f32_e32 v246, v204, v202
	v_add_f32_e32 v247, v207, v208
	v_add_f32_e32 v251, v206, v205
	v_add_f32_e32 v252, v209, v212
	v_add_f32_e32 v253, v172, v253
	v_add_f32_e32 v243, v173, v243
	v_mfma_f32_32x32x16_bf16 v[64:79], v[68:71], v[140:143], v[226:241]
	v_add_f32_e32 v244, v170, v244
	v_add_f32_e32 v245, v171, v245
	v_add_f32_e32 v246, v158, v246
	v_add_f32_e32 v247, v159, v247
	v_add_f32_e32 v251, v152, v251
	v_add_f32_e32 v252, v153, v252
	v_mfma_f32_32x32x16_bf16 v[80:95], v[214:217], v[136:139], v[80:95]
	v_add_f32_e32 v253, v150, v253
	v_add_f32_e32 v243, v151, v243
	v_add_f32_e32 v244, v148, v244
	v_add_f32_e32 v245, v149, v245
	v_add_f32_e32 v246, v146, v246
	v_add_f32_e32 v247, v147, v247
	v_mfma_f32_32x32x16_bf16 v[64:79], v[218:221], v[136:139], v[64:79]
	v_add_f32_e32 v251, v154, v251
	v_add_f32_e32 v252, v155, v252
	v_add_f32_e32 v253, v253, v243
	v_add_f32_e32 v244, v244, v245
	v_add_f32_e32 v246, v246, v247
	v_add_f32_e32 v251, v251, v252
	ds_read_b128 v[214:217], v193 offset:24576
	ds_read_b128 v[218:221], v193 offset:36864
	s_waitcnt lgkmcnt(0)
	v_mfma_f32_32x32x16_bf16 v[80:95], v[214:217], v[132:135], v[80:95]
	v_add_f32_e32 v253, v253, v244
	v_add_f32_e32 v246, v246, v251
	v_add_f32_e32 v158, v253, v246
	v_cvt_pk_bf16_f32 v144, v145, v210
	v_cvt_pk_bf16_f32 v145, v208, v212
	v_cvt_pk_bf16_f32 v147, v207, v209
	v_mfma_f32_32x32x16_bf16 v[64:79], v[218:221], v[132:135], v[64:79]
	ds_read_b128 v[214:217], v192 offset:24576
	ds_read_b128 v[218:221], v192 offset:36864
	s_waitcnt lgkmcnt(0)
	v_mfma_f32_32x32x16_bf16 v[80:95], v[214:217], v[128:131], v[80:95]
	v_mfma_f32_32x32x16_bf16 v[64:79], v[218:221], v[128:131], v[64:79]
	ds_read_b128 v[214:217], v169 offset:24704
	ds_read_b128 v[218:221], v169 offset:36992
	s_waitcnt lgkmcnt(0)
	v_mfma_f32_32x32x16_bf16 v[80:95], v[214:217], v[124:127], v[80:95]
	v_mfma_f32_32x32x16_bf16 v[64:79], v[218:221], v[124:127], v[64:79]
	ds_read_b128 v[214:217], v190 offset:24704
	ds_read_b128 v[218:221], v190 offset:36992
	s_waitcnt lgkmcnt(0)
	v_mfma_f32_32x32x16_bf16 v[80:95], v[214:217], v[120:123], v[80:95]
	v_mfma_f32_32x32x16_bf16 v[64:79], v[218:221], v[120:123], v[64:79]
	ds_read_b128 v[214:217], v193 offset:24704
	ds_read_b128 v[218:221], v193 offset:36992
	s_waitcnt lgkmcnt(0)
	v_mfma_f32_32x32x16_bf16 v[80:95], v[214:217], v[116:119], v[80:95]
	v_mfma_f32_32x32x16_bf16 v[64:79], v[218:221], v[116:119], v[64:79]
	ds_read_b128 v[214:217], v192 offset:24704
	ds_read_b128 v[218:221], v192 offset:36992
	s_waitcnt lgkmcnt(0)
	v_mfma_f32_32x32x16_bf16 v[80:95], v[214:217], v[112:115], v[80:95]
	v_mfma_f32_32x32x16_bf16 v[64:79], v[218:221], v[112:115], v[64:79]
	ds_read_b128 v[214:217], v169 offset:24832
	ds_read_b128 v[218:221], v169 offset:37120
	s_waitcnt lgkmcnt(0)
	v_mfma_f32_32x32x16_bf16 v[80:95], v[214:217], v[108:111], v[80:95]
	v_mfma_f32_32x32x16_bf16 v[64:79], v[218:221], v[108:111], v[64:79]
	ds_read_b128 v[214:217], v190 offset:24832
	ds_read_b128 v[218:221], v190 offset:37120
	s_waitcnt lgkmcnt(0)
	v_mfma_f32_32x32x16_bf16 v[80:95], v[214:217], v[104:107], v[80:95]
	v_mfma_f32_32x32x16_bf16 v[64:79], v[218:221], v[104:107], v[64:79]
	ds_read_b128 v[214:217], v193 offset:24832
	ds_read_b128 v[218:221], v193 offset:37120
	s_waitcnt lgkmcnt(0)
	v_mfma_f32_32x32x16_bf16 v[80:95], v[214:217], v[100:103], v[80:95]
	v_mfma_f32_32x32x16_bf16 v[64:79], v[218:221], v[100:103], v[64:79]
	ds_read_b128 v[214:217], v192 offset:24832
	ds_read_b128 v[218:221], v192 offset:37120
	s_waitcnt lgkmcnt(0)
	v_mfma_f32_32x32x16_bf16 v[80:95], v[214:217], v[96:99], v[80:95]
	v_mov_b32_e32 v214, v159
	v_mov_b32_e32 v215, v152
	v_mov_b32_e32 v216, v153
	v_mov_b32_e32 v217, v150
	v_mov_b32_e32 v159, v158
	v_cvt_pk_bf16_f32 v150, v199, v201
	v_mfma_f32_32x32x16_bf16 v[64:79], v[218:221], v[96:99], v[64:79]
	v_mov_b32_e32 v218, v151
	v_mov_b32_e32 v219, v148
	v_mov_b32_e32 v220, v149
	v_mov_b32_e32 v221, v146
	v_cvt_pk_bf16_f32 v146, v211, v213
	v_cvt_pk_bf16_f32 v148, v200, v203
	v_cvt_pk_bf16_f32 v149, v202, v205
	v_cvt_pk_bf16_f32 v151, v204, v206
	v_cvt_pk_bf16_f32 v152, v172, v173
	v_cvt_pk_bf16_f32 v153, v170, v171
	v_cvt_pk_bf16_f32 v154, v196, v214
	s_nop 1
	v_permlane32_swap_b32_e32 v158, v159
	v_cvt_pk_bf16_f32 v155, v215, v216
	v_cvt_pk_bf16_f32 v170, v217, v218
	v_cvt_pk_bf16_f32 v171, v219, v220
	v_cvt_pk_bf16_f32 v172, v221, v222
	v_cvt_pk_bf16_f32 v173, v223, v224
	v_readlane_b32 s58, v249, 37
	v_readlane_b32 s59, v249, 38
	s_add_u32 s56, s58, s47
	s_addc_u32 s57, s59, s50
	s_add_u32 s4, s56, 0x17060000
	s_addc_u32 s5, s57, 0
	s_add_u32 s58, s58, s14
	s_addc_u32 s59, s59, s15
	s_add_u32 s60, s58, 0x1a040000
	s_mov_b32 m0, s41
	s_addc_u32 s61, s59, 0
	s_lshl_b32 s52, s54, 14
	s_add_i32 s62, s40, s52
	global_load_lds_dwordx4 v188, s[4:5]
	s_mov_b32 m0, s42
	s_nop 0
	global_load_lds_dwordx4 v189, s[4:5]
	s_add_i32 m0, s41, 0x4000
	s_nop 0
	global_load_lds_dwordx4 v191, s[4:5]
	s_mov_b32 m0, s62
	s_nop 0
	global_load_lds_dwordx4 v194, s[60:61]
	s_add_i32 m0, s62, 0x2000
	s_nop 0
	global_load_lds_dwordx4 v195, s[60:61]
	s_lshl_b32 s60, s43, 14
	v_add_u32_e32 v196, s60, v167
	ds_read_b64_tr_b16 v[200:201], v196 offset:0
	ds_read_b64_tr_b16 v[202:203], v196 offset:0x800
	ds_read_b64_tr_b16 v[204:205], v196 offset:0x1000
	ds_read_b64_tr_b16 v[206:207], v196 offset:0x1800
	ds_read_b64_tr_b16 v[208:209], v196 offset:0x2000
	ds_read_b64_tr_b16 v[210:211], v196 offset:0x2800
	ds_read_b64_tr_b16 v[212:213], v196 offset:0x3000
	ds_read_b64_tr_b16 v[214:215], v196 offset:0x3800
	s_waitcnt lgkmcnt(0)
; #define SBAR() __builtin_amdgcn_sched_barrier(0)
; template <int MLA>
; __device__ __forceinline__ void partialSM(f32x16& p0, f32x16& p1, float& m_reg, float& mn, float& alpha) {
;     ...
;   float pmax = p0[0];
; #pragma unroll
;   for (int r = 1; r < 16; ++r) pmax = fmaxf(pmax, p0[r]);
; #pragma unroll
;   for (int r = 0; r < 16; ++r) pmax = fmaxf(pmax, p1[r]);
;   { auto rr = __builtin_amdgcn_permlane32_swap(__float_as_uint(pmax), __float_as_uint(pmax), false, false);
;     pmax = fmaxf(__uint_as_float(rr[0]), __uint_as_float(rr[1])); }
;   if (__builtin_expect(__all(pmax - m_reg <= THR / SCALE), 1)) { mn = m_reg; alpha = 1.f; }
;   else { mn = fmaxf(m_reg, pmax); alpha = __builtin_amdgcn_exp2f((m_reg - mn) * C); m_reg = mn; }
;   float mnC = -mn * C;
; #pragma unroll
;   for (int r = 0; r < 16; ++r) p0[r] = fmaf(p0[r], C, mnC);
; #pragma unroll
;   for (int r = 0; r < 16; ++r) p1[r] = fmaf(p1[r], C, mnC);
; template <int D0> __device__ __forceinline__ void pv_one_t(f32x16& od, int vb, bf16x8 pa0, bf16x8 pa1, bf16x8 pa2, bf16x8 pa3) {
;   const s16x4 l0 = tr_read<v_rd_off(D0, 0, 0)>(vb), h0 = tr_read<v_rd_off(D0, 0, 1)>(vb), l1 = tr_read<v_rd_off(D0, 1, 0)>(vb), h1 = tr_read<v_rd_off(D0, 1, 1)>(vb);
;   const s16x4 l2 = tr_read<v_rd_off(D0, 2, 0)>(vb), h2 = tr_read<v_rd_off(D0, 2, 1)>(vb), l3 = tr_read<v_rd_off(D0, 3, 0)>(vb), h3 = tr_read<v_rd_off(D0, 3, 1)>(vb);
;   asm volatile("s_waitcnt lgkmcnt(0)" ::: "memory"); SBAR();
;     ...
;   od = __builtin_amdgcn_mfma_f32_32x32x16_bf16(PK(l0, h0), pa0, od, 0, 0, 0);
;   od = __builtin_amdgcn_mfma_f32_32x32x16_bf16(PK(l1, h1), pa1, od, 0, 0, 0);
;   od = __builtin_amdgcn_mfma_f32_32x32x16_bf16(PK(l2, h2), pa2, od, 0, 0, 0);
;   od = __builtin_amdgcn_mfma_f32_32x32x16_bf16(PK(l3, h3), pa3, od, 0, 0, 0);
;     ...
; }
; __device__ __forceinline__ void pv_d0_t(f32x16* o, int vb, bf16x8 pa0, bf16x8 pa1, bf16x8 pa2, bf16x8 pa3) {
;   pv_one_t<0>(o[0], vb, pa0, pa1, pa2, pa3); pv_one_t<1>(o[1], vb, pa0, pa1, pa2, pa3); pv_one_t<2>(o[2], vb, pa0, pa1, pa2, pa3); pv_one_t<3>(o[3], vb, pa0, pa1, pa2, pa3);
; }
	s_nop 0
	v_mfma_f32_32x32x16_bf16 v[0:15], v[200:203], v[144:147], v[0:15]
	ds_read_b64_tr_b16 v[200:201], v196 offset:0x200
	ds_read_b64_tr_b16 v[202:203], v196 offset:0xa00
	v_mfma_f32_32x32x16_bf16 v[0:15], v[204:207], v[148:151], v[0:15]
	ds_read_b64_tr_b16 v[204:205], v196 offset:0x1200
	ds_read_b64_tr_b16 v[206:207], v196 offset:0x1a00
	v_mfma_f32_32x32x16_bf16 v[0:15], v[208:211], v[152:155], v[0:15]
	ds_read_b64_tr_b16 v[208:209], v196 offset:0x2200
	ds_read_b64_tr_b16 v[210:211], v196 offset:0x2a00
	v_mfma_f32_32x32x16_bf16 v[0:15], v[212:215], v[170:173], v[0:15]
	ds_read_b64_tr_b16 v[212:213], v196 offset:0x3200
	ds_read_b64_tr_b16 v[214:215], v196 offset:0x3a00
	s_waitcnt lgkmcnt(0)
	v_mfma_f32_32x32x16_bf16 v[48:63], v[200:203], v[144:147], v[48:63]
	ds_read_b64_tr_b16 v[200:201], v196 offset:0x400
	ds_read_b64_tr_b16 v[202:203], v196 offset:0xc00
	v_mfma_f32_32x32x16_bf16 v[48:63], v[204:207], v[148:151], v[48:63]
	ds_read_b64_tr_b16 v[204:205], v196 offset:0x1400
	ds_read_b64_tr_b16 v[206:207], v196 offset:0x1c00
	v_mfma_f32_32x32x16_bf16 v[48:63], v[208:211], v[152:155], v[48:63]
	ds_read_b64_tr_b16 v[208:209], v196 offset:0x2400
	ds_read_b64_tr_b16 v[210:211], v196 offset:0x2c00
	v_mfma_f32_32x32x16_bf16 v[48:63], v[212:215], v[170:173], v[48:63]
	ds_read_b64_tr_b16 v[212:213], v196 offset:0x3400
	ds_read_b64_tr_b16 v[214:215], v196 offset:0x3c00
	s_waitcnt lgkmcnt(0)
	v_mfma_f32_32x32x16_bf16 v[32:47], v[200:203], v[144:147], v[32:47]
	ds_read_b64_tr_b16 v[200:201], v196 offset:0x600
	ds_read_b64_tr_b16 v[202:203], v196 offset:0xe00
	v_mfma_f32_32x32x16_bf16 v[32:47], v[204:207], v[148:151], v[32:47]
	ds_read_b64_tr_b16 v[204:205], v196 offset:0x1600
	ds_read_b64_tr_b16 v[206:207], v196 offset:0x1e00
	v_mfma_f32_32x32x16_bf16 v[32:47], v[208:211], v[152:155], v[32:47]
	ds_read_b64_tr_b16 v[208:209], v196 offset:0x2600
	ds_read_b64_tr_b16 v[210:211], v196 offset:0x2e00
	v_mfma_f32_32x32x16_bf16 v[32:47], v[212:215], v[170:173], v[32:47]
	ds_read_b64_tr_b16 v[212:213], v196 offset:0x3600
	ds_read_b64_tr_b16 v[214:215], v196 offset:0x3e00
	s_waitcnt lgkmcnt(0)
	v_mfma_f32_32x32x16_bf16 v[16:31], v[200:203], v[144:147], v[16:31]
	v_max_f32_e32 v144, v80, v81
	v_max3_f32 v144, v144, v82, v83
	v_max3_f32 v144, v144, v84, v85
	v_max3_f32 v144, v144, v86, v87
	v_max3_f32 v144, v144, v88, v89
	v_max3_f32 v144, v144, v90, v91
	v_max3_f32 v144, v144, v92, v93
	v_mfma_f32_32x32x16_bf16 v[16:31], v[204:207], v[148:151], v[16:31]
	v_max3_f32 v144, v144, v94, v95
	v_max3_f32 v144, v144, v64, v65
	v_max3_f32 v144, v144, v66, v67
	v_max3_f32 v144, v144, v68, v69
	v_max3_f32 v144, v144, v70, v71
	v_max3_f32 v144, v144, v72, v73
	v_max3_f32 v144, v144, v74, v75
	v_max3_f32 v144, v144, v76, v77
	v_mfma_f32_32x32x16_bf16 v[16:31], v[208:211], v[152:155], v[16:31]
	v_max3_f32 v144, v144, v78, v79
	v_mov_b32_e32 v145, v144
	s_nop 1
	v_permlane32_swap_b32_e32 v144, v145
	v_max_f32_e32 v144, v144, v145
	v_cmp_ge_f32_e32 vcc, s63, v144
	v_mfma_f32_32x32x16_bf16 v[16:31], v[212:215], v[170:173], v[16:31]
	s_cmp_eq_u64 vcc, exec
	s_cselect_b64 s[4:5], -1, 0
	s_waitcnt vmcnt(0) lgkmcnt(0)
	s_barrier
	s_cbranch_scc1 .Lal_c_m1
	v_max_f32_e32 v242, 0, v144
	v_exp_f32_e64 v152, -v242
	s_nop 0
	v_pk_mul_f32 v[14:15], v[14:15], v[152:153] op_sel_hi:[1,0]
	v_pk_mul_f32 v[12:13], v[12:13], v[152:153] op_sel_hi:[1,0]
	v_pk_mul_f32 v[10:11], v[10:11], v[152:153] op_sel_hi:[1,0]
	v_pk_mul_f32 v[8:9], v[8:9], v[152:153] op_sel_hi:[1,0]
	v_pk_mul_f32 v[6:7], v[6:7], v[152:153] op_sel_hi:[1,0]
	v_pk_mul_f32 v[4:5], v[4:5], v[152:153] op_sel_hi:[1,0]
	v_pk_mul_f32 v[2:3], v[2:3], v[152:153] op_sel_hi:[1,0]
	v_pk_mul_f32 v[0:1], v[0:1], v[152:153] op_sel_hi:[1,0]
	v_pk_mul_f32 v[62:63], v[62:63], v[152:153] op_sel_hi:[1,0]
	v_pk_mul_f32 v[60:61], v[60:61], v[152:153] op_sel_hi:[1,0]
	v_pk_mul_f32 v[58:59], v[58:59], v[152:153] op_sel_hi:[1,0]
	v_pk_mul_f32 v[56:57], v[56:57], v[152:153] op_sel_hi:[1,0]
	v_pk_mul_f32 v[54:55], v[54:55], v[152:153] op_sel_hi:[1,0]
	v_pk_mul_f32 v[52:53], v[52:53], v[152:153] op_sel_hi:[1,0]
	v_pk_mul_f32 v[50:51], v[50:51], v[152:153] op_sel_hi:[1,0]
	v_pk_mul_f32 v[48:49], v[48:49], v[152:153] op_sel_hi:[1,0]
	v_pk_mul_f32 v[46:47], v[46:47], v[152:153] op_sel_hi:[1,0]
	v_pk_mul_f32 v[44:45], v[44:45], v[152:153] op_sel_hi:[1,0]
	v_pk_mul_f32 v[42:43], v[42:43], v[152:153] op_sel_hi:[1,0]
	v_pk_mul_f32 v[40:41], v[40:41], v[152:153] op_sel_hi:[1,0]
	v_pk_mul_f32 v[38:39], v[38:39], v[152:153] op_sel_hi:[1,0]
	v_pk_mul_f32 v[36:37], v[36:37], v[152:153] op_sel_hi:[1,0]
	v_pk_mul_f32 v[34:35], v[34:35], v[152:153] op_sel_hi:[1,0]
	v_pk_mul_f32 v[32:33], v[32:33], v[152:153] op_sel_hi:[1,0]
	v_pk_mul_f32 v[30:31], v[30:31], v[152:153] op_sel_hi:[1,0]
	v_pk_mul_f32 v[28:29], v[28:29], v[152:153] op_sel_hi:[1,0]
	v_pk_mul_f32 v[26:27], v[26:27], v[152:153] op_sel_hi:[1,0]
	v_pk_mul_f32 v[24:25], v[24:25], v[152:153] op_sel_hi:[1,0]
	v_pk_mul_f32 v[22:23], v[22:23], v[152:153] op_sel_hi:[1,0]
	v_pk_mul_f32 v[20:21], v[20:21], v[152:153] op_sel_hi:[1,0]
	v_pk_mul_f32 v[18:19], v[18:19], v[152:153] op_sel_hi:[1,0]
	v_pk_mul_f32 v[16:17], v[16:17], v[152:153] op_sel_hi:[1,0]
	v_sub_f32_e32 v80, v80, v242
	v_sub_f32_e32 v81, v81, v242
	v_sub_f32_e32 v82, v82, v242
	v_sub_f32_e32 v83, v83, v242
	v_sub_f32_e32 v84, v84, v242
	v_sub_f32_e32 v85, v85, v242
	v_sub_f32_e32 v86, v86, v242
	v_sub_f32_e32 v87, v87, v242
	v_sub_f32_e32 v88, v88, v242
	v_sub_f32_e32 v89, v89, v242
	v_sub_f32_e32 v90, v90, v242
	v_sub_f32_e32 v91, v91, v242
	v_sub_f32_e32 v92, v92, v242
	v_sub_f32_e32 v93, v93, v242
	v_sub_f32_e32 v94, v94, v242
	v_sub_f32_e32 v95, v95, v242
	v_sub_f32_e32 v64, v64, v242
	v_sub_f32_e32 v65, v65, v242
	v_sub_f32_e32 v66, v66, v242
	v_sub_f32_e32 v67, v67, v242
	v_sub_f32_e32 v68, v68, v242
	v_sub_f32_e32 v69, v69, v242
	v_sub_f32_e32 v70, v70, v242
	v_sub_f32_e32 v71, v71, v242
	v_sub_f32_e32 v72, v72, v242
	v_sub_f32_e32 v73, v73, v242
	v_sub_f32_e32 v74, v74, v242
	v_sub_f32_e32 v75, v75, v242
	v_sub_f32_e32 v76, v76, v242
	v_sub_f32_e32 v77, v77, v242
	v_sub_f32_e32 v78, v78, v242
	v_sub_f32_e32 v79, v79, v242
	v_sub_f32_e32 v226, v226, v242
	v_sub_f32_e32 v227, v227, v242
	v_sub_f32_e32 v228, v228, v242
	v_sub_f32_e32 v229, v229, v242
	v_sub_f32_e32 v230, v230, v242
	v_sub_f32_e32 v231, v231, v242
	v_sub_f32_e32 v232, v232, v242
	v_sub_f32_e32 v233, v233, v242
	v_sub_f32_e32 v234, v234, v242
	v_sub_f32_e32 v235, v235, v242
	v_sub_f32_e32 v236, v236, v242
	v_sub_f32_e32 v237, v237, v242
	v_sub_f32_e32 v238, v238, v242
	v_sub_f32_e32 v239, v239, v242
	v_sub_f32_e32 v240, v240, v242
	v_sub_f32_e32 v241, v241, v242
	s_branch .LBB0_117

; __device__ __forceinline__ void finishSM(f32x16& p0, f32x16& p1, float alpha, float& l_reg, bf16x8& pa0, bf16x8& pa1, bf16x8& pa2, bf16x8& pa3) {
; #pragma unroll
;   for (int r = 0; r < 16; ++r) p1[r] = __builtin_amdgcn_exp2f(p1[r]);
;   float ps = 0;
; #pragma unroll
;   for (int r = 0; r < 16; ++r) ps += p0[r];
; #pragma unroll
;   for (int r = 0; r < 16; ++r) ps += p1[r];
;   { auto rr = __builtin_amdgcn_permlane32_swap(__float_as_uint(ps), __float_as_uint(ps), false, false);
;     ps = __uint_as_float(rr[0]) + __uint_as_float(rr[1]); }
;   l_reg = l_reg * alpha + ps;
;     ...
;   PK4(p0, 0, pa0); PK4(p0, 8, pa1); PK4(p1, 0, pa2); PK4(p1, 8, pa3);
;     ...
; }
; template <int BUFOFF>
; __device__ __forceinline__ void qkt_mla(f32x16& p0, f32x16& p1, const int* ka, const bf16x8* qr, const char* qlds) {
;   typedef __attribute__((address_space(3))) const bf16x8* lp;
;   p0 = f32x16{}; p1 = f32x16{};
; #pragma unroll
;   for (int d0 = 0; d0 < 12; ++d0) {
;     const int a = ka[d0 & 3] + (d0 >> 2) * 128 + BUFOFF;
;     const bf16x8 b0 = *(lp)(a), b1 = *(lp)(a + 12288);
;     bf16x8 qf;
;     qf = qr[d0];
;     p0 = __builtin_amdgcn_mfma_f32_32x32x16_bf16(b0, qf, p0, 0, 0, 0);
;     p1 = __builtin_amdgcn_mfma_f32_32x32x16_bf16(b1, qf, p1, 0, 0, 0);
;   }
; }
.LBB0_117:
	v_exp_f32_e32 v155, v64
	v_exp_f32_e32 v170, v65
	v_exp_f32_e32 v171, v66
	v_exp_f32_e32 v172, v67
	v_exp_f32_e32 v173, v68
	v_exp_f32_e32 v197, v69
	v_exp_f32_e32 v199, v70
	v_exp_f32_e32 v200, v71
	v_exp_f32_e32 v201, v72
	v_exp_f32_e32 v202, v73
	v_exp_f32_e32 v203, v74
	v_exp_f32_e32 v204, v75
	v_exp_f32_e32 v205, v76
	v_exp_f32_e32 v222, v77
	v_exp_f32_e32 v223, v78
	v_exp_f32_e32 v154, v79
	v_exp_f32_e32 v206, v80
	v_exp_f32_e32 v207, v81
	v_exp_f32_e32 v208, v82
	v_exp_f32_e32 v209, v83
	v_exp_f32_e32 v210, v84
	v_exp_f32_e32 v211, v85
	v_exp_f32_e32 v212, v86
	v_exp_f32_e32 v213, v87
	v_exp_f32_e32 v214, v88
	v_exp_f32_e32 v215, v89
	v_exp_f32_e32 v216, v90
	v_exp_f32_e32 v217, v91
	v_exp_f32_e32 v218, v92
	v_exp_f32_e32 v219, v93
	v_exp_f32_e32 v220, v94
	v_exp_f32_e32 v221, v95
	ds_read_b128 v[64:67], v169
	ds_read_b128 v[68:71], v169 offset:12288
	ds_read_b128 v[144:147], v190
	ds_read_b128 v[148:151], v190 offset:12288
	v_mov_b32_e32 v224, v155
	v_mov_b32_e32 v225, v154
	v_add_f32_e32 v253, v218, v214
	v_add_f32_e32 v243, v210, v206
	v_add_f32_e32 v244, v219, v215
	v_add_f32_e32 v245, v211, v207
	v_add_f32_e32 v246, v220, v216
	v_add_f32_e32 v247, v212, v208
	v_add_f32_e32 v251, v221, v217
	s_waitcnt lgkmcnt(0)
	v_mfma_f32_32x32x16_bf16 v[80:95], v[64:67], v[140:143], v[226:241]
	v_add_f32_e32 v252, v213, v209
	v_add_f32_e32 v253, v155, v253
	v_add_f32_e32 v243, v170, v243
	v_add_f32_e32 v244, v171, v244
	v_add_f32_e32 v245, v172, v245
	v_add_f32_e32 v246, v173, v246
	v_mfma_f32_32x32x16_bf16 v[64:79], v[68:71], v[140:143], v[226:241]
	v_add_f32_e32 v247, v197, v247
	v_add_f32_e32 v251, v199, v251
	v_add_f32_e32 v252, v200, v252
	v_add_f32_e32 v253, v201, v253
	v_add_f32_e32 v243, v202, v243
	v_add_f32_e32 v244, v203, v244
	v_mfma_f32_32x32x16_bf16 v[80:95], v[144:147], v[136:139], v[80:95]
	v_add_f32_e32 v245, v204, v245
	v_add_f32_e32 v246, v205, v246
	v_add_f32_e32 v247, v222, v247
	v_add_f32_e32 v251, v223, v251
	v_add_f32_e32 v252, v154, v252
	v_add_f32_e32 v253, v253, v243
	v_mfma_f32_32x32x16_bf16 v[64:79], v[148:151], v[136:139], v[64:79]
	v_add_f32_e32 v244, v244, v245
	v_add_f32_e32 v246, v246, v247
	v_add_f32_e32 v251, v251, v252
	v_add_f32_e32 v253, v253, v244
	v_add_f32_e32 v246, v246, v251
	v_add_f32_e32 v154, v253, v246
	ds_read_b128 v[144:147], v193
	ds_read_b128 v[148:151], v193 offset:12288
	s_waitcnt lgkmcnt(0)
	v_mfma_f32_32x32x16_bf16 v[80:95], v[144:147], v[132:135], v[80:95]
	v_mov_b32_e32 v155, v154
	s_nop 1
	v_permlane32_swap_b32_e32 v154, v155
	v_cvt_pk_bf16_f32 v170, v224, v170
	v_cvt_pk_bf16_f32 v171, v171, v172
	v_cvt_pk_bf16_f32 v172, v173, v197
	v_cvt_pk_bf16_f32 v173, v199, v200
	v_mfma_f32_32x32x16_bf16 v[64:79], v[148:151], v[132:135], v[64:79]
	v_cvt_pk_bf16_f32 v200, v201, v202
	v_cvt_pk_bf16_f32 v201, v203, v204
	v_cvt_pk_bf16_f32 v202, v205, v222
	v_cvt_pk_bf16_f32 v203, v223, v225
	ds_read_b128 v[144:147], v192
	ds_read_b128 v[148:151], v192 offset:12288
	s_waitcnt lgkmcnt(0)
	v_mfma_f32_32x32x16_bf16 v[80:95], v[144:147], v[128:131], v[80:95]
	v_mfma_f32_32x32x16_bf16 v[64:79], v[148:151], v[128:131], v[64:79]
	ds_read_b128 v[144:147], v169 offset:128
	ds_read_b128 v[148:151], v169 offset:12416
	s_waitcnt lgkmcnt(0)
	v_mfma_f32_32x32x16_bf16 v[80:95], v[144:147], v[124:127], v[80:95]
	v_mfma_f32_32x32x16_bf16 v[64:79], v[148:151], v[124:127], v[64:79]
	ds_read_b128 v[144:147], v190 offset:128
	ds_read_b128 v[148:151], v190 offset:12416
	s_waitcnt lgkmcnt(0)
	v_mfma_f32_32x32x16_bf16 v[80:95], v[144:147], v[120:123], v[80:95]
	v_mfma_f32_32x32x16_bf16 v[64:79], v[148:151], v[120:123], v[64:79]
	ds_read_b128 v[144:147], v193 offset:128
	ds_read_b128 v[148:151], v193 offset:12416
	s_waitcnt lgkmcnt(0)
	v_mfma_f32_32x32x16_bf16 v[80:95], v[144:147], v[116:119], v[80:95]
	v_mfma_f32_32x32x16_bf16 v[64:79], v[148:151], v[116:119], v[64:79]
	ds_read_b128 v[144:147], v192 offset:128
	ds_read_b128 v[148:151], v192 offset:12416
	s_waitcnt lgkmcnt(0)
	v_mfma_f32_32x32x16_bf16 v[80:95], v[144:147], v[112:115], v[80:95]
	v_mfma_f32_32x32x16_bf16 v[64:79], v[148:151], v[112:115], v[64:79]
	ds_read_b128 v[144:147], v169 offset:256
	ds_read_b128 v[148:151], v169 offset:12544
	s_waitcnt lgkmcnt(0)
	v_mfma_f32_32x32x16_bf16 v[80:95], v[144:147], v[108:111], v[80:95]
	v_mfma_f32_32x32x16_bf16 v[64:79], v[148:151], v[108:111], v[64:79]
	ds_read_b128 v[144:147], v190 offset:256
	ds_read_b128 v[148:151], v190 offset:12544
	s_waitcnt lgkmcnt(0)
	v_mfma_f32_32x32x16_bf16 v[80:95], v[144:147], v[104:107], v[80:95]
	v_mfma_f32_32x32x16_bf16 v[64:79], v[148:151], v[104:107], v[64:79]
	ds_read_b128 v[144:147], v193 offset:256
	ds_read_b128 v[148:151], v193 offset:12544
	s_waitcnt lgkmcnt(0)
	v_mfma_f32_32x32x16_bf16 v[80:95], v[144:147], v[100:103], v[80:95]
	v_mfma_f32_32x32x16_bf16 v[64:79], v[148:151], v[100:103], v[64:79]
	ds_read_b128 v[144:147], v192 offset:256
	ds_read_b128 v[148:151], v192 offset:12544
	s_waitcnt lgkmcnt(0)
	v_mfma_f32_32x32x16_bf16 v[80:95], v[144:147], v[96:99], v[80:95]
	v_cvt_pk_bf16_f32 v144, v206, v207
	v_cvt_pk_bf16_f32 v145, v208, v209
	v_cvt_pk_bf16_f32 v146, v210, v211
	v_cvt_pk_bf16_f32 v147, v212, v213
	v_mfma_f32_32x32x16_bf16 v[64:79], v[148:151], v[96:99], v[64:79]
	v_cvt_pk_bf16_f32 v148, v214, v215
	v_cvt_pk_bf16_f32 v149, v216, v217
	v_cvt_pk_bf16_f32 v150, v218, v219
	v_cvt_pk_bf16_f32 v151, v220, v221
	s_nop 0
	s_add_u32 s4, s56, 0x17090000
	s_addc_u32 s5, s57, 0
	s_add_u32 s56, s58, 0x1a060000
	s_mov_b32 m0, s16
	s_addc_u32 s57, s59, 0
	s_add_i32 s58, s40, s60
	global_load_lds_dwordx4 v188, s[4:5]
	s_mov_b32 m0, s17
	s_nop 0
	global_load_lds_dwordx4 v189, s[4:5]
	s_mov_b32 m0, s44
	s_nop 0
	global_load_lds_dwordx4 v191, s[4:5]
	s_mov_b32 m0, s58
	s_nop 0
	global_load_lds_dwordx4 v194, s[56:57]
	s_add_i32 m0, s58, 0x2000
	s_nop 0
	global_load_lds_dwordx4 v195, s[56:57]
	v_lshl_add_u32 v197, s55, 14, v167
	ds_read_b64_tr_b16 v[204:205], v197 offset:0
	ds_read_b64_tr_b16 v[206:207], v197 offset:0x800
	ds_read_b64_tr_b16 v[208:209], v197 offset:0x1000
	ds_read_b64_tr_b16 v[210:211], v197 offset:0x1800
	ds_read_b64_tr_b16 v[212:213], v197 offset:0x2000
	ds_read_b64_tr_b16 v[214:215], v197 offset:0x2800
	ds_read_b64_tr_b16 v[216:217], v197 offset:0x3000
	ds_read_b64_tr_b16 v[218:219], v197 offset:0x3800
	s_waitcnt lgkmcnt(0)
; #define SBAR() __builtin_amdgcn_sched_barrier(0)
; template <int MLA>
; __device__ __forceinline__ void partialSM(f32x16& p0, f32x16& p1, float& m_reg, float& mn, float& alpha) {
;     ...
;   float pmax = p0[0];
; #pragma unroll
;   for (int r = 1; r < 16; ++r) pmax = fmaxf(pmax, p0[r]);
; #pragma unroll
;   for (int r = 0; r < 16; ++r) pmax = fmaxf(pmax, p1[r]);
;   { auto rr = __builtin_amdgcn_permlane32_swap(__float_as_uint(pmax), __float_as_uint(pmax), false, false);
;     pmax = fmaxf(__uint_as_float(rr[0]), __uint_as_float(rr[1])); }
;   if (__builtin_expect(__all(pmax - m_reg <= THR / SCALE), 1)) { mn = m_reg; alpha = 1.f; }
;   else { mn = fmaxf(m_reg, pmax); alpha = __builtin_amdgcn_exp2f((m_reg - mn) * C); m_reg = mn; }
;   float mnC = -mn * C;
; #pragma unroll
;   for (int r = 0; r < 16; ++r) p0[r] = fmaf(p0[r], C, mnC);
; #pragma unroll
;   for (int r = 0; r < 16; ++r) p1[r] = fmaf(p1[r], C, mnC);
; template <int D0> __device__ __forceinline__ void pv_one_t(f32x16& od, int vb, bf16x8 pa0, bf16x8 pa1, bf16x8 pa2, bf16x8 pa3) {
;   const s16x4 l0 = tr_read<v_rd_off(D0, 0, 0)>(vb), h0 = tr_read<v_rd_off(D0, 0, 1)>(vb), l1 = tr_read<v_rd_off(D0, 1, 0)>(vb), h1 = tr_read<v_rd_off(D0, 1, 1)>(vb);
;   const s16x4 l2 = tr_read<v_rd_off(D0, 2, 0)>(vb), h2 = tr_read<v_rd_off(D0, 2, 1)>(vb), l3 = tr_read<v_rd_off(D0, 3, 0)>(vb), h3 = tr_read<v_rd_off(D0, 3, 1)>(vb);
;   asm volatile("s_waitcnt lgkmcnt(0)" ::: "memory"); SBAR();
;     ...
;   od = __builtin_amdgcn_mfma_f32_32x32x16_bf16(PK(l0, h0), pa0, od, 0, 0, 0);
;   od = __builtin_amdgcn_mfma_f32_32x32x16_bf16(PK(l1, h1), pa1, od, 0, 0, 0);
;   od = __builtin_amdgcn_mfma_f32_32x32x16_bf16(PK(l2, h2), pa2, od, 0, 0, 0);
;   od = __builtin_amdgcn_mfma_f32_32x32x16_bf16(PK(l3, h3), pa3, od, 0, 0, 0);
;     ...
; }
; __device__ __forceinline__ void pv_d0_t(f32x16* o, int vb, bf16x8 pa0, bf16x8 pa1, bf16x8 pa2, bf16x8 pa3) {
;   pv_one_t<0>(o[0], vb, pa0, pa1, pa2, pa3); pv_one_t<1>(o[1], vb, pa0, pa1, pa2, pa3); pv_one_t<2>(o[2], vb, pa0, pa1, pa2, pa3); pv_one_t<3>(o[3], vb, pa0, pa1, pa2, pa3);
; }
	s_nop 0
	v_mfma_f32_32x32x16_bf16 v[0:15], v[204:207], v[144:147], v[0:15]
	ds_read_b64_tr_b16 v[204:205], v197 offset:0x200
	ds_read_b64_tr_b16 v[206:207], v197 offset:0xa00
	v_mfma_f32_32x32x16_bf16 v[0:15], v[208:211], v[148:151], v[0:15]
	ds_read_b64_tr_b16 v[208:209], v197 offset:0x1200
	ds_read_b64_tr_b16 v[210:211], v197 offset:0x1a00
	v_mfma_f32_32x32x16_bf16 v[0:15], v[212:215], v[170:173], v[0:15]
	ds_read_b64_tr_b16 v[212:213], v197 offset:0x2200
	ds_read_b64_tr_b16 v[214:215], v197 offset:0x2a00
	v_mfma_f32_32x32x16_bf16 v[0:15], v[216:219], v[200:203], v[0:15]
	ds_read_b64_tr_b16 v[216:217], v197 offset:0x3200
	ds_read_b64_tr_b16 v[218:219], v197 offset:0x3a00
	s_waitcnt lgkmcnt(0)
	v_mfma_f32_32x32x16_bf16 v[48:63], v[204:207], v[144:147], v[48:63]
	ds_read_b64_tr_b16 v[204:205], v197 offset:0x400
	ds_read_b64_tr_b16 v[206:207], v197 offset:0xc00
	v_mfma_f32_32x32x16_bf16 v[48:63], v[208:211], v[148:151], v[48:63]
	ds_read_b64_tr_b16 v[208:209], v197 offset:0x1400
	ds_read_b64_tr_b16 v[210:211], v197 offset:0x1c00
	v_mfma_f32_32x32x16_bf16 v[48:63], v[212:215], v[170:173], v[48:63]
	ds_read_b64_tr_b16 v[212:213], v197 offset:0x2400
	ds_read_b64_tr_b16 v[214:215], v197 offset:0x2c00
	v_mfma_f32_32x32x16_bf16 v[48:63], v[216:219], v[200:203], v[48:63]
	ds_read_b64_tr_b16 v[216:217], v197 offset:0x3400
	ds_read_b64_tr_b16 v[218:219], v197 offset:0x3c00
	s_waitcnt lgkmcnt(0)
	v_mfma_f32_32x32x16_bf16 v[32:47], v[204:207], v[144:147], v[32:47]
	ds_read_b64_tr_b16 v[204:205], v197 offset:0x600
	ds_read_b64_tr_b16 v[206:207], v197 offset:0xe00
	v_mfma_f32_32x32x16_bf16 v[32:47], v[208:211], v[148:151], v[32:47]
	ds_read_b64_tr_b16 v[208:209], v197 offset:0x1600
	ds_read_b64_tr_b16 v[210:211], v197 offset:0x1e00
	v_mfma_f32_32x32x16_bf16 v[32:47], v[212:215], v[170:173], v[32:47]
	ds_read_b64_tr_b16 v[212:213], v197 offset:0x2600
	ds_read_b64_tr_b16 v[214:215], v197 offset:0x2e00
	v_mfma_f32_32x32x16_bf16 v[32:47], v[216:219], v[200:203], v[32:47]
	ds_read_b64_tr_b16 v[216:217], v197 offset:0x3600
	ds_read_b64_tr_b16 v[218:219], v197 offset:0x3e00
	s_waitcnt lgkmcnt(0)
	v_mfma_f32_32x32x16_bf16 v[16:31], v[204:207], v[144:147], v[16:31]
	v_max_f32_e32 v144, v80, v81
	v_max3_f32 v144, v144, v82, v83
	v_max3_f32 v144, v144, v84, v85
	v_max3_f32 v144, v144, v86, v87
	v_max3_f32 v144, v144, v88, v89
	v_max3_f32 v144, v144, v90, v91
	v_max3_f32 v144, v144, v92, v93
	v_mfma_f32_32x32x16_bf16 v[16:31], v[208:211], v[148:151], v[16:31]
	v_max3_f32 v144, v144, v94, v95
	v_max3_f32 v144, v144, v64, v65
	v_max3_f32 v144, v144, v66, v67
	v_max3_f32 v144, v144, v68, v69
	v_max3_f32 v144, v144, v70, v71
	v_max3_f32 v144, v144, v72, v73
	v_max3_f32 v144, v144, v74, v75
	v_max3_f32 v144, v144, v76, v77
	v_mfma_f32_32x32x16_bf16 v[16:31], v[212:215], v[170:173], v[16:31]
	v_max3_f32 v144, v144, v78, v79
	v_mov_b32_e32 v145, v144
	s_nop 1
	v_permlane32_swap_b32_e32 v144, v145
	v_max_f32_e32 v144, v144, v145
	v_cmp_ge_f32_e32 vcc, s63, v144
	v_mfma_f32_32x32x16_bf16 v[16:31], v[216:219], v[200:203], v[16:31]
	s_cmp_eq_u64 vcc, exec
	s_cselect_b64 s[4:5], -1, 0
	s_waitcnt vmcnt(0) lgkmcnt(0)
	s_barrier
	s_cbranch_scc1 .Lal_c_m2
	v_max_f32_e32 v242, 0, v144
	v_exp_f32_e64 v144, -v242
	s_nop 0
	v_pk_mul_f32 v[14:15], v[14:15], v[144:145] op_sel_hi:[1,0]
	v_pk_mul_f32 v[12:13], v[12:13], v[144:145] op_sel_hi:[1,0]
	v_pk_mul_f32 v[10:11], v[10:11], v[144:145] op_sel_hi:[1,0]
	v_pk_mul_f32 v[8:9], v[8:9], v[144:145] op_sel_hi:[1,0]
	v_pk_mul_f32 v[6:7], v[6:7], v[144:145] op_sel_hi:[1,0]
	v_pk_mul_f32 v[4:5], v[4:5], v[144:145] op_sel_hi:[1,0]
	v_pk_mul_f32 v[2:3], v[2:3], v[144:145] op_sel_hi:[1,0]
	v_pk_mul_f32 v[0:1], v[0:1], v[144:145] op_sel_hi:[1,0]
	v_pk_mul_f32 v[62:63], v[62:63], v[144:145] op_sel_hi:[1,0]
	v_pk_mul_f32 v[60:61], v[60:61], v[144:145] op_sel_hi:[1,0]
	v_pk_mul_f32 v[58:59], v[58:59], v[144:145] op_sel_hi:[1,0]
	v_pk_mul_f32 v[56:57], v[56:57], v[144:145] op_sel_hi:[1,0]
	v_pk_mul_f32 v[54:55], v[54:55], v[144:145] op_sel_hi:[1,0]
	v_pk_mul_f32 v[52:53], v[52:53], v[144:145] op_sel_hi:[1,0]
	v_pk_mul_f32 v[50:51], v[50:51], v[144:145] op_sel_hi:[1,0]
	v_pk_mul_f32 v[48:49], v[48:49], v[144:145] op_sel_hi:[1,0]
	v_pk_mul_f32 v[46:47], v[46:47], v[144:145] op_sel_hi:[1,0]
	v_pk_mul_f32 v[44:45], v[44:45], v[144:145] op_sel_hi:[1,0]
	v_pk_mul_f32 v[42:43], v[42:43], v[144:145] op_sel_hi:[1,0]
	v_pk_mul_f32 v[40:41], v[40:41], v[144:145] op_sel_hi:[1,0]
	v_pk_mul_f32 v[38:39], v[38:39], v[144:145] op_sel_hi:[1,0]
	v_pk_mul_f32 v[36:37], v[36:37], v[144:145] op_sel_hi:[1,0]
	v_pk_mul_f32 v[34:35], v[34:35], v[144:145] op_sel_hi:[1,0]
	v_pk_mul_f32 v[32:33], v[32:33], v[144:145] op_sel_hi:[1,0]
	v_pk_mul_f32 v[30:31], v[30:31], v[144:145] op_sel_hi:[1,0]
	v_pk_mul_f32 v[28:29], v[28:29], v[144:145] op_sel_hi:[1,0]
	v_pk_mul_f32 v[26:27], v[26:27], v[144:145] op_sel_hi:[1,0]
	v_pk_mul_f32 v[24:25], v[24:25], v[144:145] op_sel_hi:[1,0]
	v_pk_mul_f32 v[22:23], v[22:23], v[144:145] op_sel_hi:[1,0]
	v_pk_mul_f32 v[20:21], v[20:21], v[144:145] op_sel_hi:[1,0]
	v_pk_mul_f32 v[18:19], v[18:19], v[144:145] op_sel_hi:[1,0]
	v_pk_mul_f32 v[16:17], v[16:17], v[144:145] op_sel_hi:[1,0]
	v_sub_f32_e32 v80, v80, v242
	v_sub_f32_e32 v81, v81, v242
	v_sub_f32_e32 v82, v82, v242
	v_sub_f32_e32 v83, v83, v242
	v_sub_f32_e32 v84, v84, v242
	v_sub_f32_e32 v85, v85, v242
	v_sub_f32_e32 v86, v86, v242
	v_sub_f32_e32 v87, v87, v242
	v_sub_f32_e32 v88, v88, v242
	v_sub_f32_e32 v89, v89, v242
	v_sub_f32_e32 v90, v90, v242
	v_sub_f32_e32 v91, v91, v242
	v_sub_f32_e32 v92, v92, v242
	v_sub_f32_e32 v93, v93, v242
	v_sub_f32_e32 v94, v94, v242
	v_sub_f32_e32 v95, v95, v242
	v_sub_f32_e32 v64, v64, v242
	v_sub_f32_e32 v65, v65, v242
	v_sub_f32_e32 v66, v66, v242
	v_sub_f32_e32 v67, v67, v242
	v_sub_f32_e32 v68, v68, v242
	v_sub_f32_e32 v69, v69, v242
	v_sub_f32_e32 v70, v70, v242
	v_sub_f32_e32 v71, v71, v242
	v_sub_f32_e32 v72, v72, v242
	v_sub_f32_e32 v73, v73, v242
	v_sub_f32_e32 v74, v74, v242
	v_sub_f32_e32 v75, v75, v242
	v_sub_f32_e32 v76, v76, v242
	v_sub_f32_e32 v77, v77, v242
	v_sub_f32_e32 v78, v78, v242
	v_sub_f32_e32 v79, v79, v242
	v_sub_f32_e32 v226, v226, v242
	v_sub_f32_e32 v227, v227, v242
	v_sub_f32_e32 v228, v228, v242
	v_sub_f32_e32 v229, v229, v242
	v_sub_f32_e32 v230, v230, v242
	v_sub_f32_e32 v231, v231, v242
	v_sub_f32_e32 v232, v232, v242
	v_sub_f32_e32 v233, v233, v242
	v_sub_f32_e32 v234, v234, v242
	v_sub_f32_e32 v235, v235, v242
	v_sub_f32_e32 v236, v236, v242
	v_sub_f32_e32 v237, v237, v242
	v_sub_f32_e32 v238, v238, v242
	v_sub_f32_e32 v239, v239, v242
	v_sub_f32_e32 v240, v240, v242
	v_sub_f32_e32 v241, v241, v242
	s_branch .LBB0_119

; __device__ __forceinline__ void finishSM(f32x16& p0, f32x16& p1, float alpha, float& l_reg, bf16x8& pa0, bf16x8& pa1, bf16x8& pa2, bf16x8& pa3) {
; #pragma unroll
;   for (int r = 0; r < 16; ++r) p1[r] = __builtin_amdgcn_exp2f(p1[r]);
;   float ps = 0;
; #pragma unroll
;   for (int r = 0; r < 16; ++r) ps += p0[r];
; #pragma unroll
;   for (int r = 0; r < 16; ++r) ps += p1[r];
;   { auto rr = __builtin_amdgcn_permlane32_swap(__float_as_uint(ps), __float_as_uint(ps), false, false);
;     ps = __uint_as_float(rr[0]) + __uint_as_float(rr[1]); }
;   l_reg = l_reg * alpha + ps;
;     ...
;   PK4(p0, 0, pa0); PK4(p0, 8, pa1); PK4(p1, 0, pa2); PK4(p1, 8, pa3);
;     ...
; }
; template <int BUFOFF>
; __device__ __forceinline__ void qkt_diff(f32x16& p0, f32x16& p1, const int* ka, const bf16x8* qr) {
;   typedef __attribute__((address_space(3))) const bf16x8* lp;
;   p0 = f32x16{}; p1 = f32x16{};
; #pragma unroll
;   for (int d0 = 0; d0 < 4; ++d0) {
;     const int a = ka[d0] + BUFOFF;
;     const bf16x8 b0 = *(lp)(a), b1 = *(lp)(a + 8192);
;     p0 = __builtin_amdgcn_mfma_f32_32x32x16_bf16(b0, qr[d0], p0, 0, 0, 0);
;     p1 = __builtin_amdgcn_mfma_f32_32x32x16_bf16(b1, qr[d0], p1, 0, 0, 0);
;   }
; }
.LBB0_129:
	s_mov_b32 s54, s47
	s_mov_b32 s47, s52
	ds_read_b128 v[64:67], v138 offset:16384
	ds_read_b128 v[68:71], v138 offset:24576
	ds_read_b128 v[170:173], v141 offset:16384
	ds_read_b128 v[188:191], v141 offset:24576
	v_mov_b32_e32 v132, v124
	v_mov_b32_e32 v162, v125
	v_mov_b32_e32 v167, v120
	v_mov_b32_e32 v169, v121
	v_add_f32_e32 v253, v146, v144
	v_add_f32_e32 v243, v153, v113
	v_add_f32_e32 v244, v150, v148
	v_add_f32_e32 v245, v158, v155
	s_waitcnt lgkmcnt(0)
	v_mfma_f32_32x32x16_bf16 v[80:95], v[64:67], v[108:111], v[226:241]
	v_add_f32_e32 v246, v147, v145
	v_add_f32_e32 v247, v154, v152
	v_add_f32_e32 v251, v151, v149
	v_add_f32_e32 v252, v159, v156
	v_add_f32_e32 v253, v128, v253
	v_add_f32_e32 v243, v129, v243
	v_mfma_f32_32x32x16_bf16 v[64:79], v[68:71], v[108:111], v[226:241]
	v_add_f32_e32 v244, v126, v244
	v_add_f32_e32 v245, v127, v245
	v_add_f32_e32 v246, v124, v246
	v_add_f32_e32 v247, v125, v247
	v_add_f32_e32 v251, v120, v251
	v_add_f32_e32 v252, v121, v252
	v_mfma_f32_32x32x16_bf16 v[80:95], v[170:173], v[104:107], v[80:95]
	v_add_f32_e32 v253, v118, v253
	v_add_f32_e32 v243, v119, v243
	v_add_f32_e32 v244, v116, v244
	v_add_f32_e32 v245, v117, v245
	v_add_f32_e32 v246, v114, v246
	v_add_f32_e32 v247, v115, v247
	v_mfma_f32_32x32x16_bf16 v[64:79], v[188:191], v[104:107], v[64:79]
	v_add_f32_e32 v251, v122, v251
	v_add_f32_e32 v252, v123, v252
	v_add_f32_e32 v253, v253, v243
	v_add_f32_e32 v244, v244, v245
	v_add_f32_e32 v246, v246, v247
	v_add_f32_e32 v251, v251, v252
	ds_read_b128 v[170:173], v140 offset:16384
	ds_read_b128 v[188:191], v140 offset:24576
	s_waitcnt lgkmcnt(0)
	v_mfma_f32_32x32x16_bf16 v[80:95], v[170:173], v[100:103], v[80:95]
	v_add_f32_e32 v253, v253, v244
	v_add_f32_e32 v246, v246, v251
	v_cvt_pk_bf16_f32 v112, v113, v155
	v_cvt_pk_bf16_f32 v113, v152, v156
	v_cvt_pk_bf16_f32 v120, v144, v148
	v_cvt_pk_bf16_f32 v121, v145, v149
	v_mfma_f32_32x32x16_bf16 v[64:79], v[188:191], v[100:103], v[64:79]
	v_cvt_pk_bf16_f32 v124, v128, v129
	v_cvt_pk_bf16_f32 v125, v126, v127
	v_cvt_pk_bf16_f32 v126, v132, v162
	v_cvt_pk_bf16_f32 v127, v167, v169
	ds_read_b128 v[170:173], v139 offset:16384
	ds_read_b128 v[188:191], v139 offset:24576
	s_waitcnt lgkmcnt(0)
	v_mfma_f32_32x32x16_bf16 v[80:95], v[170:173], v[96:99], v[80:95]
	v_mov_b32_e32 v170, v118
	v_mov_b32_e32 v171, v117
	v_mov_b32_e32 v172, v114
	v_mov_b32_e32 v173, v115
	v_add_f32_e32 v117, v253, v246
	v_mov_b32_e32 v118, v117
	v_mfma_f32_32x32x16_bf16 v[64:79], v[188:191], v[96:99], v[64:79]
	v_mov_b32_e32 v188, v122
	v_mov_b32_e32 v189, v123
	v_cvt_pk_bf16_f32 v114, v153, v158
	s_nop 1
	v_permlane32_swap_b32_e32 v117, v118
	v_cvt_pk_bf16_f32 v115, v154, v159
	v_cvt_pk_bf16_f32 v122, v146, v150
	v_cvt_pk_bf16_f32 v123, v147, v151
	v_cvt_pk_bf16_f32 v144, v170, v119
	v_cvt_pk_bf16_f32 v145, v116, v171
	v_cvt_pk_bf16_f32 v146, v172, v173
	v_cvt_pk_bf16_f32 v147, v188, v189
	s_add_u32 s4, s14, 0x2000000
	s_mov_b32 m0, s43
	s_addc_u32 s5, s15, 0
	s_mov_b64 s[56:57], s[14:15]
	s_lshl_b32 s52, s53, 14
	s_add_i32 s55, s42, s52
	s_nop 0
	global_load_lds_dwordx4 v134, s[56:57]
	s_mov_b32 m0, s44
	s_nop 0
	global_load_lds_dwordx4 v135, s[56:57]
	s_mov_b32 m0, s55
	s_nop 0
	global_load_lds_dwordx4 v136, s[4:5]
	s_add_i32 m0, s55, 0x2000
	s_nop 0
	global_load_lds_dwordx4 v137, s[4:5]
	s_lshl_b32 s55, s47, 14
	v_add_u32_e32 v132, s55, v133
	ds_read_b64_tr_b16 v[148:149], v132 offset:0
	ds_read_b64_tr_b16 v[150:151], v132 offset:0x800
	ds_read_b64_tr_b16 v[152:153], v132 offset:0x1000
	ds_read_b64_tr_b16 v[154:155], v132 offset:0x1800
	ds_read_b64_tr_b16 v[170:171], v132 offset:0x2000
	ds_read_b64_tr_b16 v[172:173], v132 offset:0x2800
	ds_read_b64_tr_b16 v[188:189], v132 offset:0x3000
	ds_read_b64_tr_b16 v[190:191], v132 offset:0x3800
	s_waitcnt lgkmcnt(0)
	s_nop 0
	v_mfma_f32_32x32x16_bf16 v[32:47], v[148:151], v[112:115], v[32:47]
	ds_read_b64_tr_b16 v[148:149], v132 offset:0x200
	ds_read_b64_tr_b16 v[150:151], v132 offset:0xa00
	v_mfma_f32_32x32x16_bf16 v[32:47], v[152:155], v[120:123], v[32:47]
	ds_read_b64_tr_b16 v[152:153], v132 offset:0x1200
	ds_read_b64_tr_b16 v[154:155], v132 offset:0x1a00
	v_mfma_f32_32x32x16_bf16 v[32:47], v[170:173], v[124:127], v[32:47]
	ds_read_b64_tr_b16 v[170:171], v132 offset:0x2200
	ds_read_b64_tr_b16 v[172:173], v132 offset:0x2a00
	v_mfma_f32_32x32x16_bf16 v[32:47], v[188:191], v[144:147], v[32:47]
	ds_read_b64_tr_b16 v[188:189], v132 offset:0x3200
	ds_read_b64_tr_b16 v[190:191], v132 offset:0x3a00
	s_waitcnt lgkmcnt(0)
	v_mfma_f32_32x32x16_bf16 v[48:63], v[148:151], v[112:115], v[48:63]
	ds_read_b64_tr_b16 v[148:149], v132 offset:0x400
	ds_read_b64_tr_b16 v[150:151], v132 offset:0xc00
	v_mfma_f32_32x32x16_bf16 v[48:63], v[152:155], v[120:123], v[48:63]
	ds_read_b64_tr_b16 v[152:153], v132 offset:0x1400
	ds_read_b64_tr_b16 v[154:155], v132 offset:0x1c00
	v_mfma_f32_32x32x16_bf16 v[48:63], v[170:173], v[124:127], v[48:63]
	ds_read_b64_tr_b16 v[170:171], v132 offset:0x2400
	ds_read_b64_tr_b16 v[172:173], v132 offset:0x2c00
	v_mfma_f32_32x32x16_bf16 v[48:63], v[188:191], v[144:147], v[48:63]
	ds_read_b64_tr_b16 v[188:189], v132 offset:0x3400
	ds_read_b64_tr_b16 v[190:191], v132 offset:0x3c00
	s_waitcnt lgkmcnt(0)
	v_mfma_f32_32x32x16_bf16 v[16:31], v[148:151], v[112:115], v[16:31]
	ds_read_b64_tr_b16 v[148:149], v132 offset:0x600
	ds_read_b64_tr_b16 v[150:151], v132 offset:0xe00
	v_mfma_f32_32x32x16_bf16 v[16:31], v[152:155], v[120:123], v[16:31]
	ds_read_b64_tr_b16 v[152:153], v132 offset:0x1600
	ds_read_b64_tr_b16 v[154:155], v132 offset:0x1e00
	v_mfma_f32_32x32x16_bf16 v[16:31], v[170:173], v[124:127], v[16:31]
	ds_read_b64_tr_b16 v[170:171], v132 offset:0x2600
	ds_read_b64_tr_b16 v[172:173], v132 offset:0x2e00
	v_mfma_f32_32x32x16_bf16 v[16:31], v[188:191], v[144:147], v[16:31]
	ds_read_b64_tr_b16 v[188:189], v132 offset:0x3600
	ds_read_b64_tr_b16 v[190:191], v132 offset:0x3e00
	s_waitcnt lgkmcnt(0)
	v_mfma_f32_32x32x16_bf16 v[0:15], v[148:151], v[112:115], v[0:15]
	v_max_f32_e32 v112, v80, v81
	v_max3_f32 v112, v112, v82, v83
	v_max3_f32 v112, v112, v84, v85
	v_max3_f32 v112, v112, v86, v87
	v_max3_f32 v112, v112, v88, v89
	v_max3_f32 v112, v112, v90, v91
	v_max3_f32 v112, v112, v92, v93
	v_mfma_f32_32x32x16_bf16 v[0:15], v[152:155], v[120:123], v[0:15]
	v_max3_f32 v112, v112, v94, v95
	v_max3_f32 v112, v112, v64, v65
	v_max3_f32 v112, v112, v66, v67
	v_max3_f32 v112, v112, v68, v69
	v_max3_f32 v112, v112, v70, v71
	v_max3_f32 v112, v112, v72, v73
	v_max3_f32 v112, v112, v74, v75
	v_max3_f32 v112, v112, v76, v77
	v_mfma_f32_32x32x16_bf16 v[0:15], v[170:173], v[124:127], v[0:15]
	v_max3_f32 v112, v112, v78, v79
	v_mov_b32_e32 v113, v112
	s_nop 1
	v_permlane32_swap_b32_e32 v112, v113
	v_max_f32_e32 v112, v112, v113
	v_cmp_ge_f32_e32 vcc, s70, v112
	v_mfma_f32_32x32x16_bf16 v[0:15], v[188:191], v[144:147], v[0:15]
	s_cmp_eq_u64 vcc, exec
	s_cselect_b64 s[4:5], -1, 0
	s_waitcnt vmcnt(0) lgkmcnt(0)
	s_barrier
; template <int MLA>
; __device__ __forceinline__ void partialSM(f32x16& p0, f32x16& p1, float& m_reg, float& mn, float& alpha) {
;     ...
;   if (__builtin_expect(__all(pmax - m_reg <= THR / SCALE), 1)) { mn = m_reg; alpha = 1.f; }
;   else { mn = fmaxf(m_reg, pmax); alpha = __builtin_amdgcn_exp2f((m_reg - mn) * C); m_reg = mn; }
;   float mnC = -mn * C;
; #pragma unroll
;   for (int r = 0; r < 16; ++r) p0[r] = fmaf(p0[r], C, mnC);
; #pragma unroll
;   for (int r = 0; r < 16; ++r) p1[r] = fmaf(p1[r], C, mnC);
	s_cbranch_scc1 .Lal_c_d1
	v_max_f32_e32 v242, 0, v112
	v_exp_f32_e64 v116, -v242
	s_nop 0
	v_pk_mul_f32 v[46:47], v[46:47], v[116:117] op_sel_hi:[1,0]
	v_pk_mul_f32 v[44:45], v[44:45], v[116:117] op_sel_hi:[1,0]
	v_pk_mul_f32 v[42:43], v[42:43], v[116:117] op_sel_hi:[1,0]
	v_pk_mul_f32 v[40:41], v[40:41], v[116:117] op_sel_hi:[1,0]
	v_pk_mul_f32 v[38:39], v[38:39], v[116:117] op_sel_hi:[1,0]
	v_pk_mul_f32 v[36:37], v[36:37], v[116:117] op_sel_hi:[1,0]
	v_pk_mul_f32 v[34:35], v[34:35], v[116:117] op_sel_hi:[1,0]
	v_pk_mul_f32 v[32:33], v[32:33], v[116:117] op_sel_hi:[1,0]
	v_pk_mul_f32 v[62:63], v[62:63], v[116:117] op_sel_hi:[1,0]
	v_pk_mul_f32 v[60:61], v[60:61], v[116:117] op_sel_hi:[1,0]
	v_pk_mul_f32 v[58:59], v[58:59], v[116:117] op_sel_hi:[1,0]
	v_pk_mul_f32 v[56:57], v[56:57], v[116:117] op_sel_hi:[1,0]
	v_pk_mul_f32 v[54:55], v[54:55], v[116:117] op_sel_hi:[1,0]
	v_pk_mul_f32 v[52:53], v[52:53], v[116:117] op_sel_hi:[1,0]
	v_pk_mul_f32 v[50:51], v[50:51], v[116:117] op_sel_hi:[1,0]
	v_pk_mul_f32 v[48:49], v[48:49], v[116:117] op_sel_hi:[1,0]
	v_pk_mul_f32 v[30:31], v[30:31], v[116:117] op_sel_hi:[1,0]
	v_pk_mul_f32 v[28:29], v[28:29], v[116:117] op_sel_hi:[1,0]
	v_pk_mul_f32 v[26:27], v[26:27], v[116:117] op_sel_hi:[1,0]
	v_pk_mul_f32 v[24:25], v[24:25], v[116:117] op_sel_hi:[1,0]
	v_pk_mul_f32 v[22:23], v[22:23], v[116:117] op_sel_hi:[1,0]
	v_pk_mul_f32 v[20:21], v[20:21], v[116:117] op_sel_hi:[1,0]
	v_pk_mul_f32 v[18:19], v[18:19], v[116:117] op_sel_hi:[1,0]
	v_pk_mul_f32 v[16:17], v[16:17], v[116:117] op_sel_hi:[1,0]
	v_pk_mul_f32 v[14:15], v[14:15], v[116:117] op_sel_hi:[1,0]
	v_pk_mul_f32 v[12:13], v[12:13], v[116:117] op_sel_hi:[1,0]
	v_pk_mul_f32 v[10:11], v[10:11], v[116:117] op_sel_hi:[1,0]
	v_pk_mul_f32 v[8:9], v[8:9], v[116:117] op_sel_hi:[1,0]
	v_pk_mul_f32 v[6:7], v[6:7], v[116:117] op_sel_hi:[1,0]
	v_pk_mul_f32 v[4:5], v[4:5], v[116:117] op_sel_hi:[1,0]
	v_pk_mul_f32 v[2:3], v[2:3], v[116:117] op_sel_hi:[1,0]
	v_pk_mul_f32 v[0:1], v[0:1], v[116:117] op_sel_hi:[1,0]
	v_sub_f32_e32 v80, v80, v242
	v_sub_f32_e32 v81, v81, v242
	v_sub_f32_e32 v82, v82, v242
	v_sub_f32_e32 v83, v83, v242
	v_sub_f32_e32 v84, v84, v242
	v_sub_f32_e32 v85, v85, v242
	v_sub_f32_e32 v86, v86, v242
	v_sub_f32_e32 v87, v87, v242
	v_sub_f32_e32 v88, v88, v242
	v_sub_f32_e32 v89, v89, v242
	v_sub_f32_e32 v90, v90, v242
	v_sub_f32_e32 v91, v91, v242
	v_sub_f32_e32 v92, v92, v242
	v_sub_f32_e32 v93, v93, v242
	v_sub_f32_e32 v94, v94, v242
	v_sub_f32_e32 v95, v95, v242
	v_sub_f32_e32 v64, v64, v242
	v_sub_f32_e32 v65, v65, v242
	v_sub_f32_e32 v66, v66, v242
	v_sub_f32_e32 v67, v67, v242
	v_sub_f32_e32 v68, v68, v242
	v_sub_f32_e32 v69, v69, v242
	v_sub_f32_e32 v70, v70, v242
	v_sub_f32_e32 v71, v71, v242
	v_sub_f32_e32 v72, v72, v242
	v_sub_f32_e32 v73, v73, v242
	v_sub_f32_e32 v74, v74, v242
	v_sub_f32_e32 v75, v75, v242
	v_sub_f32_e32 v76, v76, v242
	v_sub_f32_e32 v77, v77, v242
	v_sub_f32_e32 v78, v78, v242
	v_sub_f32_e32 v79, v79, v242
	v_sub_f32_e32 v226, v226, v242
	v_sub_f32_e32 v227, v227, v242
	v_sub_f32_e32 v228, v228, v242
	v_sub_f32_e32 v229, v229, v242
	v_sub_f32_e32 v230, v230, v242
	v_sub_f32_e32 v231, v231, v242
	v_sub_f32_e32 v232, v232, v242
	v_sub_f32_e32 v233, v233, v242
	v_sub_f32_e32 v234, v234, v242
	v_sub_f32_e32 v235, v235, v242
	v_sub_f32_e32 v236, v236, v242
	v_sub_f32_e32 v237, v237, v242
	v_sub_f32_e32 v238, v238, v242
	v_sub_f32_e32 v239, v239, v242
	v_sub_f32_e32 v240, v240, v242
	v_sub_f32_e32 v241, v241, v242
	s_branch .LBB0_131

; __device__ __forceinline__ void finishSM(f32x16& p0, f32x16& p1, float alpha, float& l_reg, bf16x8& pa0, bf16x8& pa1, bf16x8& pa2, bf16x8& pa3) {
; #pragma unroll
;   for (int r = 0; r < 16; ++r) p1[r] = __builtin_amdgcn_exp2f(p1[r]);
;   float ps = 0;
; #pragma unroll
;   for (int r = 0; r < 16; ++r) ps += p0[r];
; #pragma unroll
;   for (int r = 0; r < 16; ++r) ps += p1[r];
;   { auto rr = __builtin_amdgcn_permlane32_swap(__float_as_uint(ps), __float_as_uint(ps), false, false);
;     ps = __uint_as_float(rr[0]) + __uint_as_float(rr[1]); }
;   l_reg = l_reg * alpha + ps;
;     ...
;   PK4(p0, 0, pa0); PK4(p0, 8, pa1); PK4(p1, 0, pa2); PK4(p1, 8, pa3);
;     ...
; }
; template <int BUFOFF>
; __device__ __forceinline__ void qkt_diff(f32x16& p0, f32x16& p1, const int* ka, const bf16x8* qr) {
;   typedef __attribute__((address_space(3))) const bf16x8* lp;
;   p0 = f32x16{}; p1 = f32x16{};
; #pragma unroll
;   for (int d0 = 0; d0 < 4; ++d0) {
;     const int a = ka[d0] + BUFOFF;
;     const bf16x8 b0 = *(lp)(a), b1 = *(lp)(a + 8192);
;     p0 = __builtin_amdgcn_mfma_f32_32x32x16_bf16(b0, qr[d0], p0, 0, 0, 0);
;     p1 = __builtin_amdgcn_mfma_f32_32x32x16_bf16(b1, qr[d0], p1, 0, 0, 0);
;   }
; }
.LBB0_131:
	v_exp_f32_e32 v125, v64
	v_exp_f32_e32 v126, v65
	v_exp_f32_e32 v127, v66
	v_exp_f32_e32 v128, v67
	v_exp_f32_e32 v129, v68
	v_exp_f32_e32 v143, v69
	v_exp_f32_e32 v144, v70
	v_exp_f32_e32 v145, v71
	v_exp_f32_e32 v146, v72
	v_exp_f32_e32 v147, v73
	v_exp_f32_e32 v148, v74
	v_exp_f32_e32 v149, v75
	v_exp_f32_e32 v150, v76
	v_exp_f32_e32 v151, v80
	v_exp_f32_e32 v152, v81
	v_exp_f32_e32 v153, v82
	v_exp_f32_e32 v154, v83
	v_exp_f32_e32 v155, v84
	v_exp_f32_e32 v156, v85
	v_exp_f32_e32 v158, v86
	v_exp_f32_e32 v159, v87
	v_exp_f32_e32 v162, v88
	v_exp_f32_e32 v167, v89
	v_exp_f32_e32 v169, v90
	v_exp_f32_e32 v170, v91
	v_exp_f32_e32 v171, v92
	v_exp_f32_e32 v172, v93
	v_exp_f32_e32 v173, v94
	v_exp_f32_e32 v188, v95
	v_exp_f32_e32 v189, v77
	v_exp_f32_e32 v190, v78
	v_exp_f32_e32 v124, v79
	ds_read_b128 v[64:67], v138
	ds_read_b128 v[68:71], v138 offset:8192
	ds_read_b128 v[112:115], v141
	ds_read_b128 v[120:123], v141 offset:8192
	v_mov_b32_e32 v191, v125
	v_mov_b32_e32 v192, v124
	v_add_f32_e32 v253, v171, v162
	v_add_f32_e32 v243, v155, v151
	v_add_f32_e32 v244, v172, v167
	v_add_f32_e32 v245, v156, v152
	v_add_f32_e32 v246, v173, v169
	v_add_f32_e32 v247, v158, v153
	v_add_f32_e32 v251, v188, v170
	s_waitcnt lgkmcnt(0)
	v_mfma_f32_32x32x16_bf16 v[80:95], v[64:67], v[108:111], v[226:241]
	v_add_f32_e32 v252, v159, v154
	v_add_f32_e32 v253, v125, v253
	v_add_f32_e32 v243, v126, v243
	v_add_f32_e32 v244, v127, v244
	v_add_f32_e32 v245, v128, v245
	v_add_f32_e32 v246, v129, v246
	v_mfma_f32_32x32x16_bf16 v[64:79], v[68:71], v[108:111], v[226:241]
	v_add_f32_e32 v247, v143, v247
	v_add_f32_e32 v251, v144, v251
	v_add_f32_e32 v252, v145, v252
	v_add_f32_e32 v253, v146, v253
	v_add_f32_e32 v243, v147, v243
	v_add_f32_e32 v244, v148, v244
	v_mfma_f32_32x32x16_bf16 v[80:95], v[112:115], v[104:107], v[80:95]
	v_add_f32_e32 v245, v149, v245
	v_add_f32_e32 v246, v150, v246
	v_add_f32_e32 v247, v189, v247
	v_add_f32_e32 v251, v190, v251
	v_add_f32_e32 v252, v124, v252
	v_add_f32_e32 v253, v253, v243
	v_mfma_f32_32x32x16_bf16 v[64:79], v[120:123], v[104:107], v[64:79]
	v_add_f32_e32 v244, v244, v245
	v_add_f32_e32 v246, v246, v247
	v_add_f32_e32 v251, v251, v252
	v_add_f32_e32 v253, v253, v244
	v_add_f32_e32 v246, v246, v251
	v_cvt_pk_bf16_f32 v124, v171, v172
	ds_read_b128 v[112:115], v140
	ds_read_b128 v[120:123], v140 offset:8192
	s_waitcnt lgkmcnt(0)
	v_mfma_f32_32x32x16_bf16 v[80:95], v[112:115], v[100:103], v[80:95]
	v_cvt_pk_bf16_f32 v125, v173, v188
	v_cvt_pk_bf16_f32 v126, v191, v126
	v_cvt_pk_bf16_f32 v127, v127, v128
	v_cvt_pk_bf16_f32 v128, v129, v143
	v_cvt_pk_bf16_f32 v129, v144, v145
	v_cvt_pk_bf16_f32 v144, v146, v147
	v_mfma_f32_32x32x16_bf16 v[64:79], v[120:123], v[100:103], v[64:79]
	v_cvt_pk_bf16_f32 v145, v148, v149
	v_cvt_pk_bf16_f32 v146, v150, v189
	v_cvt_pk_bf16_f32 v147, v190, v192
	ds_read_b128 v[112:115], v139
	ds_read_b128 v[120:123], v139 offset:8192
	s_waitcnt lgkmcnt(0)
	v_mfma_f32_32x32x16_bf16 v[80:95], v[112:115], v[96:99], v[80:95]
	v_cvt_pk_bf16_f32 v112, v151, v152
	v_cvt_pk_bf16_f32 v113, v153, v154
	v_cvt_pk_bf16_f32 v114, v155, v156
	v_cvt_pk_bf16_f32 v115, v158, v159
	v_mfma_f32_32x32x16_bf16 v[64:79], v[120:123], v[96:99], v[64:79]
	v_add_f32_e32 v120, v253, v246
	v_mov_b32_e32 v121, v120
	s_nop 1
	v_permlane32_swap_b32_e32 v120, v121
	v_cvt_pk_bf16_f32 v122, v162, v167
	v_cvt_pk_bf16_f32 v123, v169, v170
	s_nop 0
	s_add_u32 s4, s14, 0x20000
	s_addc_u32 s5, s15, 0
	s_add_u32 s56, s14, 0x2020000
	s_mov_b32 m0, s16
	s_addc_u32 s57, s15, 0
	s_add_i32 s55, s42, s55
	s_nop 0
	global_load_lds_dwordx4 v134, s[4:5]
	s_mov_b32 m0, s17
	s_nop 0
	global_load_lds_dwordx4 v135, s[4:5]
	s_mov_b32 m0, s55
	s_nop 0
	global_load_lds_dwordx4 v136, s[56:57]
	s_add_i32 m0, s55, 0x2000
	s_nop 0
	global_load_lds_dwordx4 v137, s[56:57]
	v_lshl_add_u32 v143, s54, 14, v133
	ds_read_b64_tr_b16 v[148:149], v143 offset:0
	ds_read_b64_tr_b16 v[150:151], v143 offset:0x800
	ds_read_b64_tr_b16 v[152:153], v143 offset:0x1000
	ds_read_b64_tr_b16 v[154:155], v143 offset:0x1800
	ds_read_b64_tr_b16 v[170:171], v143 offset:0x2000
	ds_read_b64_tr_b16 v[172:173], v143 offset:0x2800
	ds_read_b64_tr_b16 v[188:189], v143 offset:0x3000
	ds_read_b64_tr_b16 v[190:191], v143 offset:0x3800
	s_waitcnt lgkmcnt(0)
	s_nop 0
	v_mfma_f32_32x32x16_bf16 v[32:47], v[148:151], v[112:115], v[32:47]
	ds_read_b64_tr_b16 v[148:149], v143 offset:0x200
	ds_read_b64_tr_b16 v[150:151], v143 offset:0xa00
	v_mfma_f32_32x32x16_bf16 v[32:47], v[152:155], v[122:125], v[32:47]
	ds_read_b64_tr_b16 v[152:153], v143 offset:0x1200
	ds_read_b64_tr_b16 v[154:155], v143 offset:0x1a00
	v_mfma_f32_32x32x16_bf16 v[32:47], v[170:173], v[126:129], v[32:47]
	ds_read_b64_tr_b16 v[170:171], v143 offset:0x2200
	ds_read_b64_tr_b16 v[172:173], v143 offset:0x2a00
	v_mfma_f32_32x32x16_bf16 v[32:47], v[188:191], v[144:147], v[32:47]
	ds_read_b64_tr_b16 v[188:189], v143 offset:0x3200
	ds_read_b64_tr_b16 v[190:191], v143 offset:0x3a00
	s_waitcnt lgkmcnt(0)
	v_mfma_f32_32x32x16_bf16 v[48:63], v[148:151], v[112:115], v[48:63]
	ds_read_b64_tr_b16 v[148:149], v143 offset:0x400
	ds_read_b64_tr_b16 v[150:151], v143 offset:0xc00
	v_mfma_f32_32x32x16_bf16 v[48:63], v[152:155], v[122:125], v[48:63]
	ds_read_b64_tr_b16 v[152:153], v143 offset:0x1400
	ds_read_b64_tr_b16 v[154:155], v143 offset:0x1c00
	v_mfma_f32_32x32x16_bf16 v[48:63], v[170:173], v[126:129], v[48:63]
	ds_read_b64_tr_b16 v[170:171], v143 offset:0x2400
	ds_read_b64_tr_b16 v[172:173], v143 offset:0x2c00
	v_mfma_f32_32x32x16_bf16 v[48:63], v[188:191], v[144:147], v[48:63]
	ds_read_b64_tr_b16 v[188:189], v143 offset:0x3400
	ds_read_b64_tr_b16 v[190:191], v143 offset:0x3c00
	s_waitcnt lgkmcnt(0)
; #define SBAR() __builtin_amdgcn_sched_barrier(0)
; template <int MLA>
; __device__ __forceinline__ void partialSM(f32x16& p0, f32x16& p1, float& m_reg, float& mn, float& alpha) {
;     ...
;   float pmax = p0[0];
; #pragma unroll
;   for (int r = 1; r < 16; ++r) pmax = fmaxf(pmax, p0[r]);
; #pragma unroll
;   for (int r = 0; r < 16; ++r) pmax = fmaxf(pmax, p1[r]);
;   { auto rr = __builtin_amdgcn_permlane32_swap(__float_as_uint(pmax), __float_as_uint(pmax), false, false);
;     pmax = fmaxf(__uint_as_float(rr[0]), __uint_as_float(rr[1])); }
;   if (__builtin_expect(__all(pmax - m_reg <= THR / SCALE), 1)) { mn = m_reg; alpha = 1.f; }
;   else { mn = fmaxf(m_reg, pmax); alpha = __builtin_amdgcn_exp2f((m_reg - mn) * C); m_reg = mn; }
;   float mnC = -mn * C;
; #pragma unroll
;   for (int r = 0; r < 16; ++r) p0[r] = fmaf(p0[r], C, mnC);
; #pragma unroll
;   for (int r = 0; r < 16; ++r) p1[r] = fmaf(p1[r], C, mnC);
; template <int D0> __device__ __forceinline__ void pv_one_t(f32x16& od, int vb, bf16x8 pa0, bf16x8 pa1, bf16x8 pa2, bf16x8 pa3) {
;   const s16x4 l0 = tr_read<v_rd_off(D0, 0, 0)>(vb), h0 = tr_read<v_rd_off(D0, 0, 1)>(vb), l1 = tr_read<v_rd_off(D0, 1, 0)>(vb), h1 = tr_read<v_rd_off(D0, 1, 1)>(vb);
;   const s16x4 l2 = tr_read<v_rd_off(D0, 2, 0)>(vb), h2 = tr_read<v_rd_off(D0, 2, 1)>(vb), l3 = tr_read<v_rd_off(D0, 3, 0)>(vb), h3 = tr_read<v_rd_off(D0, 3, 1)>(vb);
;   asm volatile("s_waitcnt lgkmcnt(0)" ::: "memory"); SBAR();
;     ...
;   od = __builtin_amdgcn_mfma_f32_32x32x16_bf16(PK(l0, h0), pa0, od, 0, 0, 0);
;   od = __builtin_amdgcn_mfma_f32_32x32x16_bf16(PK(l1, h1), pa1, od, 0, 0, 0);
;   od = __builtin_amdgcn_mfma_f32_32x32x16_bf16(PK(l2, h2), pa2, od, 0, 0, 0);
;   od = __builtin_amdgcn_mfma_f32_32x32x16_bf16(PK(l3, h3), pa3, od, 0, 0, 0);
;     ...
; }
; __device__ __forceinline__ void pv_d0_t(f32x16* o, int vb, bf16x8 pa0, bf16x8 pa1, bf16x8 pa2, bf16x8 pa3) {
;   pv_one_t<0>(o[0], vb, pa0, pa1, pa2, pa3); pv_one_t<1>(o[1], vb, pa0, pa1, pa2, pa3); pv_one_t<2>(o[2], vb, pa0, pa1, pa2, pa3); pv_one_t<3>(o[3], vb, pa0, pa1, pa2, pa3);
; }
	v_mfma_f32_32x32x16_bf16 v[16:31], v[148:151], v[112:115], v[16:31]
	ds_read_b64_tr_b16 v[148:149], v143 offset:0x600
	ds_read_b64_tr_b16 v[150:151], v143 offset:0xe00
	v_mfma_f32_32x32x16_bf16 v[16:31], v[152:155], v[122:125], v[16:31]
	ds_read_b64_tr_b16 v[152:153], v143 offset:0x1600
	ds_read_b64_tr_b16 v[154:155], v143 offset:0x1e00
	v_mfma_f32_32x32x16_bf16 v[16:31], v[170:173], v[126:129], v[16:31]
	ds_read_b64_tr_b16 v[170:171], v143 offset:0x2600
	ds_read_b64_tr_b16 v[172:173], v143 offset:0x2e00
	v_mfma_f32_32x32x16_bf16 v[16:31], v[188:191], v[144:147], v[16:31]
	ds_read_b64_tr_b16 v[188:189], v143 offset:0x3600
	ds_read_b64_tr_b16 v[190:191], v143 offset:0x3e00
	s_waitcnt lgkmcnt(0)
	v_mfma_f32_32x32x16_bf16 v[0:15], v[148:151], v[112:115], v[0:15]
	v_max_f32_e32 v112, v80, v81
	v_max3_f32 v112, v112, v82, v83
	v_max3_f32 v112, v112, v84, v85
	v_max3_f32 v112, v112, v86, v87
	v_max3_f32 v112, v112, v88, v89
	v_max3_f32 v112, v112, v90, v91
	v_max3_f32 v112, v112, v92, v93
	v_mfma_f32_32x32x16_bf16 v[0:15], v[152:155], v[122:125], v[0:15]
	v_max3_f32 v112, v112, v94, v95
	v_max3_f32 v112, v112, v64, v65
	v_max3_f32 v112, v112, v66, v67
	v_max3_f32 v112, v112, v68, v69
	v_max3_f32 v112, v112, v70, v71
	v_max3_f32 v112, v112, v72, v73
	v_max3_f32 v112, v112, v74, v75
	v_max3_f32 v112, v112, v76, v77
	v_mfma_f32_32x32x16_bf16 v[0:15], v[170:173], v[126:129], v[0:15]
	v_max3_f32 v112, v112, v78, v79
	v_mov_b32_e32 v113, v112
	s_nop 1
	v_permlane32_swap_b32_e32 v112, v113
	v_max_f32_e32 v112, v112, v113
	v_cmp_ge_f32_e32 vcc, s70, v112
	v_mfma_f32_32x32x16_bf16 v[0:15], v[188:191], v[144:147], v[0:15]
	s_cmp_eq_u64 vcc, exec
	s_cselect_b64 s[4:5], -1, 0
	s_waitcnt vmcnt(0) lgkmcnt(0)
	s_barrier
	s_cbranch_scc1 .Lal_c_d2
	v_max_f32_e32 v242, 0, v112
	v_exp_f32_e64 v112, -v242
	s_nop 0
	v_pk_mul_f32 v[46:47], v[46:47], v[112:113] op_sel_hi:[1,0]
	v_pk_mul_f32 v[44:45], v[44:45], v[112:113] op_sel_hi:[1,0]
	v_pk_mul_f32 v[42:43], v[42:43], v[112:113] op_sel_hi:[1,0]
	v_pk_mul_f32 v[40:41], v[40:41], v[112:113] op_sel_hi:[1,0]
	v_pk_mul_f32 v[38:39], v[38:39], v[112:113] op_sel_hi:[1,0]
	v_pk_mul_f32 v[36:37], v[36:37], v[112:113] op_sel_hi:[1,0]
	v_pk_mul_f32 v[34:35], v[34:35], v[112:113] op_sel_hi:[1,0]
	v_pk_mul_f32 v[32:33], v[32:33], v[112:113] op_sel_hi:[1,0]
	v_pk_mul_f32 v[62:63], v[62:63], v[112:113] op_sel_hi:[1,0]
	v_pk_mul_f32 v[60:61], v[60:61], v[112:113] op_sel_hi:[1,0]
	v_pk_mul_f32 v[58:59], v[58:59], v[112:113] op_sel_hi:[1,0]
	v_pk_mul_f32 v[56:57], v[56:57], v[112:113] op_sel_hi:[1,0]
	v_pk_mul_f32 v[54:55], v[54:55], v[112:113] op_sel_hi:[1,0]
	v_pk_mul_f32 v[52:53], v[52:53], v[112:113] op_sel_hi:[1,0]
	v_pk_mul_f32 v[50:51], v[50:51], v[112:113] op_sel_hi:[1,0]
	v_pk_mul_f32 v[48:49], v[48:49], v[112:113] op_sel_hi:[1,0]
	v_pk_mul_f32 v[30:31], v[30:31], v[112:113] op_sel_hi:[1,0]
	v_pk_mul_f32 v[28:29], v[28:29], v[112:113] op_sel_hi:[1,0]
	v_pk_mul_f32 v[26:27], v[26:27], v[112:113] op_sel_hi:[1,0]
	v_pk_mul_f32 v[24:25], v[24:25], v[112:113] op_sel_hi:[1,0]
	v_pk_mul_f32 v[22:23], v[22:23], v[112:113] op_sel_hi:[1,0]
	v_pk_mul_f32 v[20:21], v[20:21], v[112:113] op_sel_hi:[1,0]
	v_pk_mul_f32 v[18:19], v[18:19], v[112:113] op_sel_hi:[1,0]
	v_pk_mul_f32 v[16:17], v[16:17], v[112:113] op_sel_hi:[1,0]
	v_pk_mul_f32 v[14:15], v[14:15], v[112:113] op_sel_hi:[1,0]
	v_pk_mul_f32 v[12:13], v[12:13], v[112:113] op_sel_hi:[1,0]
	v_pk_mul_f32 v[10:11], v[10:11], v[112:113] op_sel_hi:[1,0]
	v_pk_mul_f32 v[8:9], v[8:9], v[112:113] op_sel_hi:[1,0]
	v_pk_mul_f32 v[6:7], v[6:7], v[112:113] op_sel_hi:[1,0]
	v_pk_mul_f32 v[4:5], v[4:5], v[112:113] op_sel_hi:[1,0]
	v_pk_mul_f32 v[2:3], v[2:3], v[112:113] op_sel_hi:[1,0]
	v_pk_mul_f32 v[0:1], v[0:1], v[112:113] op_sel_hi:[1,0]
	v_sub_f32_e32 v80, v80, v242
	v_sub_f32_e32 v81, v81, v242
	v_sub_f32_e32 v82, v82, v242
	v_sub_f32_e32 v83, v83, v242
	v_sub_f32_e32 v84, v84, v242
	v_sub_f32_e32 v85, v85, v242
	v_sub_f32_e32 v86, v86, v242
	v_sub_f32_e32 v87, v87, v242
	v_sub_f32_e32 v88, v88, v242
	v_sub_f32_e32 v89, v89, v242
	v_sub_f32_e32 v90, v90, v242
	v_sub_f32_e32 v91, v91, v242
	v_sub_f32_e32 v92, v92, v242
	v_sub_f32_e32 v93, v93, v242
	v_sub_f32_e32 v94, v94, v242
	v_sub_f32_e32 v95, v95, v242
	v_sub_f32_e32 v64, v64, v242
	v_sub_f32_e32 v65, v65, v242
	v_sub_f32_e32 v66, v66, v242
	v_sub_f32_e32 v67, v67, v242
	v_sub_f32_e32 v68, v68, v242
	v_sub_f32_e32 v69, v69, v242
	v_sub_f32_e32 v70, v70, v242
	v_sub_f32_e32 v71, v71, v242
	v_sub_f32_e32 v72, v72, v242
	v_sub_f32_e32 v73, v73, v242
	v_sub_f32_e32 v74, v74, v242
	v_sub_f32_e32 v75, v75, v242
	v_sub_f32_e32 v76, v76, v242
	v_sub_f32_e32 v77, v77, v242
	v_sub_f32_e32 v78, v78, v242
	v_sub_f32_e32 v79, v79, v242
	v_sub_f32_e32 v226, v226, v242
	v_sub_f32_e32 v227, v227, v242
	v_sub_f32_e32 v228, v228, v242
	v_sub_f32_e32 v229, v229, v242
	v_sub_f32_e32 v230, v230, v242
	v_sub_f32_e32 v231, v231, v242
	v_sub_f32_e32 v232, v232, v242
	v_sub_f32_e32 v233, v233, v242
	v_sub_f32_e32 v234, v234, v242
	v_sub_f32_e32 v235, v235, v242
	v_sub_f32_e32 v236, v236, v242
	v_sub_f32_e32 v237, v237, v242
	v_sub_f32_e32 v238, v238, v242
	v_sub_f32_e32 v239, v239, v242
	v_sub_f32_e32 v240, v240, v242
	v_sub_f32_e32 v241, v241, v242
	s_branch .LBB0_133
